# differential attention role-split loop: the lagging wave half issues its K/V LDS-DMA pieces at the end of its VALU segment (beside the partner's MFMA segment) instead of inside its own MFMA segment
# speedup vs baseline: 1.0161x; 1.0161x over previous
;   #define WB(a,b) do{ if constexpr(DV2){WAIT_BAR(b);} else {WAIT_BAR(a);} }while(0)
;   #define RESC() do{ if(resc){ asm volatile("s_waitcnt lgkmcnt(0)":::"memory"); \
;       _Pragma("unroll") for(int d_=0;d_<ND;++d_) _Pragma("unroll") for(int r=0;r<16;++r)o[d_][r]*=wsf[crow(r,hi)]; } }while(0)
;   #define ROT() do{sl_prev=sl_cur;sl_cur=sl_next;sl_next=(sl_next==(NSLOT-1)*SLOTB)?0:sl_next+SLOTB;}while(0)
;     ...
;   int t=1;
;   for(;t+5<NT;t+=2){
;     STEP(pB0,pB1,pA0,pA1,t,true,true,true);     WB(2,3); RESC(); ROT();
;     STEP(pA0,pA1,pB0,pB1,t+1,true,true,true);   WB(2,3); RESC(); ROT();
;   }
.Lpqk2_entry:
	v_readfirstlane_b32 s93, v234
	s_lshr_b32 s93, s93, 8
	s_cmp_lg_u32 s93, 0
	s_cbranch_scc1 .Lpqk2B_in

;   #define WB(a,b) do{ if constexpr(DV2){WAIT_BAR(b);} else {WAIT_BAR(a);} }while(0)
;   #define RESC() do{ if(resc){ asm volatile("s_waitcnt lgkmcnt(0)":::"memory"); \
;       _Pragma("unroll") for(int d_=0;d_<ND;++d_) _Pragma("unroll") for(int r=0;r<16;++r)o[d_][r]*=wsf[crow(r,hi)]; } }while(0)
;   #define ROT() do{sl_prev=sl_cur;sl_cur=sl_next;sl_next=(sl_next==(NSLOT-1)*SLOTB)?0:sl_next+SLOTB;}while(0)
;   #define ENDW(tt) do{ if((tt)+3<NT){WB(2,3);} else if((tt)+2<NT){WB(1,2);} else {WAIT_BAR(0);} }while(0)
;     ...
;   int t=1;
;   for(;t+5<NT;t+=2){
;     STEP(pB0,pB1,pA0,pA1,t,true,true,true);     WB(2,3); RESC(); ROT();
;     STEP(pA0,pA1,pB0,pB1,t+1,true,true,true);   WB(2,3); RESC(); ROT();
;   }
;     ...
;   for(;t+1<NT;t+=2){
;     STEP(pB0,pB1,pA0,pA1,t,(t+3<NT),(t+1<NT),(t+1<NT));       ENDW(t);   RESC(); ROT();
;     STEP(pA0,pA1,pB0,pB1,t+1,(t+4<NT),(t+2<NT),(t+2<NT));     ENDW(t+1); RESC(); ROT();
;   }
;   STEP(pB0,pB1,pA0,pA1,NT-1,false,false,false); RESC();
.Lpqk2A_exit:
	s_barrier
	s_branch .LBB0_281

.Lpqk2B:
	v_add_f32_e32 v230, v98, v99
	v_cvt_pk_bf16_f32 v150, v98, v99
	v_add_f32_e32 v231, v100, v101
	v_cvt_pk_bf16_f32 v151, v100, v101
	v_add_f32_e32 v230, v102, v230
	v_add_f32_e32 v231, v103, v231
	v_add_f32_e32 v230, v104, v230
	v_cvt_pk_bf16_f32 v152, v102, v103
	v_add_f32_e32 v231, v105, v231
	v_cvt_pk_bf16_f32 v153, v104, v105
	v_add_f32_e32 v230, v106, v230
	v_add_f32_e32 v231, v107, v231
	v_add_f32_e32 v230, v108, v230
	v_cvt_pk_bf16_f32 v10, v106, v107
	v_add_f32_e32 v231, v109, v231
	v_cvt_pk_bf16_f32 v11, v108, v109
	v_add_f32_e32 v230, v110, v230
	v_add_f32_e32 v231, v111, v231
	v_add_f32_e32 v230, v112, v230
	v_cvt_pk_bf16_f32 v12, v110, v111
	v_add_f32_e32 v231, v113, v231
	v_cvt_pk_bf16_f32 v13, v112, v113
	v_add_f32_e32 v230, v82, v230
	v_add_f32_e32 v231, v83, v231
	v_add_f32_e32 v230, v84, v230
	v_cvt_pk_bf16_f32 v6, v82, v83
	v_add_f32_e32 v231, v85, v231
	v_cvt_pk_bf16_f32 v7, v84, v85
	v_add_f32_e32 v230, v86, v230
	v_add_f32_e32 v231, v87, v231
	v_add_f32_e32 v230, v88, v230
	v_cvt_pk_bf16_f32 v8, v86, v87
	v_add_f32_e32 v231, v89, v231
	v_cvt_pk_bf16_f32 v9, v88, v89
	v_add_f32_e32 v230, v90, v230
	v_add_f32_e32 v231, v91, v231
	v_add_f32_e32 v230, v92, v230
	v_cvt_pk_bf16_f32 v2, v90, v91
	v_add_f32_e32 v231, v93, v231
	v_cvt_pk_bf16_f32 v3, v92, v93
	v_add_f32_e32 v230, v94, v230
	v_add_f32_e32 v231, v95, v231
	v_add_f32_e32 v230, v96, v230
	v_cvt_pk_bf16_f32 v4, v94, v95
	v_add_f32_e32 v231, v97, v231
	v_cvt_pk_bf16_f32 v5, v96, v97
	v_add_f32_e32 v230, v230, v231
	v_add_f32_e32 v206, v232, v230
	s_add_u32 s54, s48, s14
	s_addc_u32 s55, s49, s15
	s_add_u32 s56, s54, 0x8000
	s_addc_u32 s57, s55, 0
	s_add_i32 s16, s21, s43
	s_mov_b32 m0, s16
	s_nop 0
	global_load_lds_dwordx4 v202, s[56:57]
	s_add_u32 s56, s50, s14
	s_addc_u32 s57, s51, s15
	s_add_u32 s56, s56, 0x4000
	s_addc_u32 s57, s57, 0
	s_add_i32 s16, s13, s44
	s_mov_b32 m0, s16
	s_nop 0
	global_load_lds_dwordx4 v203, s[56:57]
	s_add_u32 s58, s52, s14
	s_addc_u32 s59, s53, s15
	s_add_u32 s58, s58, 0x4000
	s_addc_u32 s59, s59, 0
	s_add_i32 s16, s13, s45
	s_mov_b32 m0, s16
	s_nop 0
	global_load_lds_dwordx4 v203, s[58:59]
	s_barrier
	s_setprio 1
	v_add_u32_e32 v0, s22, v251
	ds_read_b64_tr_b16 v[198:199], v0 offset:24576
	ds_read_b64_tr_b16 v[200:201], v0 offset:25088
	s_waitcnt lgkmcnt(9)
	v_mfma_f32_32x32x16_bf16 v[130:145], v[194:197], v[162:165], v[208:223]
	ds_read_b64_tr_b16 v[194:195], v0 offset:28672
	ds_read_b64_tr_b16 v[196:197], v0 offset:29184
	s_waitcnt lgkmcnt(10)
	v_mfma_f32_32x32x16_bf16 v[114:129], v[186:189], v[162:165], v[208:223]
	ds_read_b64_tr_b16 v[102:103], v0 offset:25600
	ds_read_b64_tr_b16 v[104:105], v0 offset:26112
	s_waitcnt lgkmcnt(11)
	v_mfma_f32_32x32x16_bf16 v[130:145], v[190:193], v[158:161], v[130:145]
	ds_read_b64_tr_b16 v[98:99], v0 offset:29696
	ds_read_b64_tr_b16 v[100:101], v0 offset:30208
	s_waitcnt lgkmcnt(12)
	v_mfma_f32_32x32x16_bf16 v[114:129], v[182:185], v[158:161], v[114:129]
	ds_read_b64_tr_b16 v[110:111], v0 offset:26624
	ds_read_b64_tr_b16 v[112:113], v0 offset:27136
	s_waitcnt lgkmcnt(13)
	v_mfma_f32_32x32x16_bf16 v[130:145], v[178:181], v[154:157], v[130:145]
	ds_read_b64_tr_b16 v[106:107], v0 offset:30720
	ds_read_b64_tr_b16 v[108:109], v0 offset:31232
	s_waitcnt lgkmcnt(14)
	v_mfma_f32_32x32x16_bf16 v[114:129], v[174:177], v[154:157], v[114:129]
	ds_read_b64_tr_b16 v[86:87], v0 offset:27648
	ds_read_b64_tr_b16 v[88:89], v0 offset:28160
	s_waitcnt lgkmcnt(14)
	v_mfma_f32_32x32x16_bf16 v[130:145], v[170:173], v[146:149], v[130:145]
	ds_read_b64_tr_b16 v[82:83], v0 offset:31744
	ds_read_b64_tr_b16 v[84:85], v0 offset:32256
	v_mfma_f32_32x32x16_bf16 v[114:129], v[166:169], v[146:149], v[114:129]
	v_add_u32_e32 v0, s22, v249
	v_add_u32_e32 v166, 0xe800, v0
	s_waitcnt lgkmcnt(14)
	v_mfma_f32_32x32x16_bf16 v[66:81], v[150:153], v[198:201], v[66:81]
	ds_read_b64_tr_b16 v[90:91], v0 offset:59392
	ds_read_b64_tr_b16 v[92:93], v0 offset:59904
	s_waitcnt lgkmcnt(14)
	v_mfma_f32_32x32x16_bf16 v[50:65], v[150:153], v[194:197], v[50:65]
	ds_read_b64_tr_b16 v[94:95], v0 offset:63488
	ds_read_b64_tr_b16 v[96:97], v0 offset:64000
	s_waitcnt lgkmcnt(14)
	v_mfma_f32_32x32x16_bf16 v[66:81], v[10:13], v[102:105], v[66:81]
	ds_read_b64_tr_b16 v[102:103], v0 offset:60416
	ds_read_b64_tr_b16 v[104:105], v0 offset:60928
	s_waitcnt lgkmcnt(14)
	v_mfma_f32_32x32x16_bf16 v[50:65], v[10:13], v[98:101], v[50:65]
	ds_read_b64_tr_b16 v[98:99], v0 offset:64512
	ds_read_b64_tr_b16 v[100:101], v0 offset:65024
	s_waitcnt lgkmcnt(14)
	v_mfma_f32_32x32x16_bf16 v[66:81], v[6:9], v[110:113], v[66:81]
	ds_read_b64_tr_b16 v[110:111], v0 offset:61440
	ds_read_b64_tr_b16 v[112:113], v0 offset:61952
	s_waitcnt lgkmcnt(14)
	v_mfma_f32_32x32x16_bf16 v[50:65], v[6:9], v[106:109], v[50:65]
	ds_read_b64_tr_b16 v[106:107], v166 offset:6144
	ds_read_b64_tr_b16 v[108:109], v166 offset:6656
	s_waitcnt lgkmcnt(14)
	v_mfma_f32_32x32x16_bf16 v[66:81], v[2:5], v[86:89], v[66:81]
	ds_read_b64_tr_b16 v[190:191], v0 offset:62464
	ds_read_b64_tr_b16 v[192:193], v0 offset:62976
	s_waitcnt lgkmcnt(14)
	v_mfma_f32_32x32x16_bf16 v[50:65], v[2:5], v[82:85], v[50:65]
	ds_read_b64_tr_b16 v[194:195], v166 offset:7168
	ds_read_b64_tr_b16 v[196:197], v166 offset:7680
	s_waitcnt lgkmcnt(14)
	v_mfma_f32_32x32x16_bf16 v[34:49], v[150:153], v[90:93], v[34:49]
	s_waitcnt lgkmcnt(12)
	v_mfma_f32_32x32x16_bf16 v[18:33], v[150:153], v[94:97], v[18:33]
	v_add_u32_e32 v0, s13, v250
	ds_read_b128 v[86:89], v0
	ds_read_b128 v[82:85], v0 offset:512
	s_waitcnt lgkmcnt(12)
	v_mfma_f32_32x32x16_bf16 v[34:49], v[10:13], v[102:105], v[34:49]
	ds_read_b128 v[186:189], v0 offset:2048
	ds_read_b128 v[182:185], v0 offset:2560
	s_waitcnt lgkmcnt(12)
	v_mfma_f32_32x32x16_bf16 v[18:33], v[10:13], v[98:101], v[18:33]
	ds_read_b128 v[178:181], v0 offset:4096
	ds_read_b128 v[174:177], v0 offset:4608
	s_waitcnt lgkmcnt(12)
	v_mfma_f32_32x32x16_bf16 v[34:49], v[6:9], v[110:113], v[34:49]
	ds_read_b128 v[170:173], v0 offset:6144
	ds_read_b128 v[166:169], v0 offset:6656
	s_waitcnt lgkmcnt(12)
	v_mfma_f32_32x32x16_bf16 v[18:33], v[6:9], v[106:109], v[18:33]
	s_waitcnt lgkmcnt(10)
	v_mfma_f32_32x32x16_bf16 v[34:49], v[2:5], v[190:193], v[34:49]
	s_waitcnt lgkmcnt(8)
	v_mfma_f32_32x32x16_bf16 v[18:33], v[2:5], v[194:197], v[18:33]
	s_setprio 0
	s_waitcnt vmcnt(3) lgkmcnt(0)
	s_barrier
	v_exp_f32_e32 v130, v130
	v_exp_f32_e32 v131, v131
	v_exp_f32_e32 v132, v132
	v_exp_f32_e32 v133, v133
	v_exp_f32_e32 v134, v134
	v_exp_f32_e32 v135, v135
	v_exp_f32_e32 v136, v136
	v_exp_f32_e32 v137, v137
	v_exp_f32_e32 v138, v138
	v_exp_f32_e32 v139, v139
	v_exp_f32_e32 v140, v140
	v_exp_f32_e32 v141, v141
	v_exp_f32_e32 v142, v142
	v_exp_f32_e32 v143, v143
	v_exp_f32_e32 v144, v144
	v_exp_f32_e32 v145, v145
	v_exp_f32_e32 v114, v114
	v_exp_f32_e32 v115, v115
	v_exp_f32_e32 v116, v116
	v_exp_f32_e32 v117, v117
	v_exp_f32_e32 v118, v118
	v_exp_f32_e32 v119, v119
	v_exp_f32_e32 v120, v120
	v_exp_f32_e32 v121, v121
	v_exp_f32_e32 v122, v122
	v_exp_f32_e32 v123, v123
	v_exp_f32_e32 v124, v124
	v_exp_f32_e32 v125, v125
	v_exp_f32_e32 v126, v126
	v_exp_f32_e32 v127, v127
	v_exp_f32_e32 v128, v128
	v_exp_f32_e32 v129, v129
	v_add_f32_e32 v230, v130, v131
	v_cvt_pk_bf16_f32 v150, v130, v131
	v_add_f32_e32 v231, v132, v133
	v_cvt_pk_bf16_f32 v151, v132, v133
	v_add_f32_e32 v230, v134, v230
	v_add_f32_e32 v231, v135, v231
	v_add_f32_e32 v230, v136, v230
	v_cvt_pk_bf16_f32 v152, v134, v135
	v_add_f32_e32 v231, v137, v231
	v_cvt_pk_bf16_f32 v153, v136, v137
	v_add_f32_e32 v230, v138, v230
	v_add_f32_e32 v231, v139, v231
	v_add_f32_e32 v230, v140, v230
	v_cvt_pk_bf16_f32 v10, v138, v139
	v_add_f32_e32 v231, v141, v231
	v_cvt_pk_bf16_f32 v11, v140, v141
	v_add_f32_e32 v230, v142, v230
	v_add_f32_e32 v231, v143, v231
	v_add_f32_e32 v230, v144, v230
	v_cvt_pk_bf16_f32 v12, v142, v143
	v_add_f32_e32 v231, v145, v231
	v_cvt_pk_bf16_f32 v13, v144, v145
	v_add_f32_e32 v230, v114, v230
	v_add_f32_e32 v231, v115, v231
	v_add_f32_e32 v230, v116, v230
	v_cvt_pk_bf16_f32 v6, v114, v115
	v_add_f32_e32 v231, v117, v231
	v_cvt_pk_bf16_f32 v7, v116, v117
	v_add_f32_e32 v230, v118, v230
	v_add_f32_e32 v231, v119, v231
	v_add_f32_e32 v230, v120, v230
	v_cvt_pk_bf16_f32 v8, v118, v119
	v_add_f32_e32 v231, v121, v231
	v_cvt_pk_bf16_f32 v9, v120, v121
	v_add_f32_e32 v230, v122, v230
	v_add_f32_e32 v231, v123, v231
	v_add_f32_e32 v230, v124, v230
	v_cvt_pk_bf16_f32 v2, v122, v123
	v_add_f32_e32 v231, v125, v231
	v_cvt_pk_bf16_f32 v3, v124, v125
	v_add_f32_e32 v230, v126, v230
	v_add_f32_e32 v231, v127, v231
	v_add_f32_e32 v230, v128, v230
	v_cvt_pk_bf16_f32 v4, v126, v127
	v_add_f32_e32 v231, v129, v231
	v_cvt_pk_bf16_f32 v5, v128, v129
	v_add_f32_e32 v230, v230, v231
	v_add_f32_e32 v232, v206, v230
	s_add_i32 s16, s13, 0x2000
	s_cmpk_lg_i32 s13, 0x4000
	s_cselect_b32 s47, s16, 0
	s_add_u32 s56, s54, 0xa000
	s_addc_u32 s57, s55, 0
	s_add_i32 s16, s13, s43
	s_mov_b32 m0, s16
	s_nop 0
	global_load_lds_dwordx4 v202, s[56:57]
	s_add_u32 s56, s50, s14
	s_addc_u32 s57, s51, s15
	s_add_u32 s56, s56, 0x6000
	s_addc_u32 s57, s57, 0
	s_add_i32 s16, s47, s44
	s_mov_b32 m0, s16
	s_nop 0
	global_load_lds_dwordx4 v203, s[56:57]
	s_add_u32 s58, s52, s14
	s_addc_u32 s59, s53, s15
	s_add_u32 s58, s58, 0x6000
	s_addc_u32 s59, s59, 0
	s_add_i32 s16, s47, s45
	s_mov_b32 m0, s16
	s_nop 0
	global_load_lds_dwordx4 v203, s[58:59]
	s_barrier
;   #define WB(a,b) do{ if constexpr(DV2){WAIT_BAR(b);} else {WAIT_BAR(a);} }while(0)
;   #define RESC() do{ if(resc){ asm volatile("s_waitcnt lgkmcnt(0)":::"memory"); \
;       _Pragma("unroll") for(int d_=0;d_<ND;++d_) _Pragma("unroll") for(int r=0;r<16;++r)o[d_][r]*=wsf[crow(r,hi)]; } }while(0)
;   #define ROT() do{sl_prev=sl_cur;sl_cur=sl_next;sl_next=(sl_next==(NSLOT-1)*SLOTB)?0:sl_next+SLOTB;}while(0)
;     ...
;   int t=1;
;   for(;t+5<NT;t+=2){
;     STEP(pB0,pB1,pA0,pA1,t,true,true,true);     WB(2,3); RESC(); ROT();
;     STEP(pA0,pA1,pB0,pB1,t+1,true,true,true);   WB(2,3); RESC(); ROT();
;   }
	s_setprio 1
	v_add_u32_e32 v207, s21, v251
	ds_read_b64_tr_b16 v[198:199], v207 offset:24576
	ds_read_b64_tr_b16 v[200:201], v207 offset:25088
	s_waitcnt lgkmcnt(9)
	v_mfma_f32_32x32x16_bf16 v[98:113], v[86:89], v[162:165], v[208:223]
	ds_read_b64_tr_b16 v[194:195], v207 offset:28672
	ds_read_b64_tr_b16 v[196:197], v207 offset:29184
	s_waitcnt lgkmcnt(10)
	v_mfma_f32_32x32x16_bf16 v[82:97], v[82:85], v[162:165], v[208:223]
	ds_read_b64_tr_b16 v[190:191], v207 offset:25600
	ds_read_b64_tr_b16 v[192:193], v207 offset:26112
	s_waitcnt lgkmcnt(11)
	v_mfma_f32_32x32x16_bf16 v[98:113], v[186:189], v[158:161], v[98:113]
	ds_read_b64_tr_b16 v[138:139], v207 offset:29696
	ds_read_b64_tr_b16 v[140:141], v207 offset:30208
	s_waitcnt lgkmcnt(12)
	v_mfma_f32_32x32x16_bf16 v[82:97], v[182:185], v[158:161], v[82:97]
	ds_read_b64_tr_b16 v[134:135], v207 offset:26624
	ds_read_b64_tr_b16 v[136:137], v207 offset:27136
	s_waitcnt lgkmcnt(13)
	v_mfma_f32_32x32x16_bf16 v[98:113], v[178:181], v[154:157], v[98:113]
	ds_read_b64_tr_b16 v[130:131], v207 offset:30720
	ds_read_b64_tr_b16 v[132:133], v207 offset:31232
	s_waitcnt lgkmcnt(14)
	v_mfma_f32_32x32x16_bf16 v[82:97], v[174:177], v[154:157], v[82:97]
	ds_read_b64_tr_b16 v[118:119], v207 offset:27648
	ds_read_b64_tr_b16 v[120:121], v207 offset:28160
	s_waitcnt lgkmcnt(14)
	v_mfma_f32_32x32x16_bf16 v[98:113], v[170:173], v[146:149], v[98:113]
	ds_read_b64_tr_b16 v[114:115], v207 offset:31744
	ds_read_b64_tr_b16 v[116:117], v207 offset:32256
	v_mfma_f32_32x32x16_bf16 v[82:97], v[166:169], v[146:149], v[82:97]
	v_add_u32_e32 v14, s21, v249
	v_add_u32_e32 v15, 0xe800, v14
	s_waitcnt lgkmcnt(14)
	v_mfma_f32_32x32x16_bf16 v[66:81], v[150:153], v[198:201], v[66:81]
	ds_read_b64_tr_b16 v[122:123], v14 offset:59392
	ds_read_b64_tr_b16 v[124:125], v14 offset:59904
	s_waitcnt lgkmcnt(14)
	v_mfma_f32_32x32x16_bf16 v[50:65], v[150:153], v[194:197], v[50:65]
	ds_read_b64_tr_b16 v[126:127], v14 offset:63488
	ds_read_b64_tr_b16 v[128:129], v14 offset:64000
	s_waitcnt lgkmcnt(14)
	v_mfma_f32_32x32x16_bf16 v[66:81], v[10:13], v[190:193], v[66:81]
	ds_read_b64_tr_b16 v[142:143], v14 offset:60416
	ds_read_b64_tr_b16 v[144:145], v14 offset:60928
	s_waitcnt lgkmcnt(14)
	v_mfma_f32_32x32x16_bf16 v[50:65], v[10:13], v[138:141], v[50:65]
	ds_read_b64_tr_b16 v[138:139], v14 offset:64512
	ds_read_b64_tr_b16 v[140:141], v14 offset:65024
	s_waitcnt lgkmcnt(14)
	v_mfma_f32_32x32x16_bf16 v[66:81], v[6:9], v[134:137], v[66:81]
	ds_read_b64_tr_b16 v[134:135], v14 offset:61440
	ds_read_b64_tr_b16 v[136:137], v14 offset:61952
	s_waitcnt lgkmcnt(14)
	v_mfma_f32_32x32x16_bf16 v[50:65], v[6:9], v[130:133], v[50:65]
	ds_read_b64_tr_b16 v[130:131], v15 offset:6144
	ds_read_b64_tr_b16 v[132:133], v15 offset:6656
	s_waitcnt lgkmcnt(14)
	v_mfma_f32_32x32x16_bf16 v[66:81], v[2:5], v[118:121], v[66:81]
	ds_read_b64_tr_b16 v[118:119], v14 offset:62464
	ds_read_b64_tr_b16 v[120:121], v14 offset:62976
	s_waitcnt lgkmcnt(14)
	v_mfma_f32_32x32x16_bf16 v[50:65], v[2:5], v[114:117], v[50:65]
	ds_read_b64_tr_b16 v[114:115], v15 offset:7168
	ds_read_b64_tr_b16 v[116:117], v15 offset:7680
	s_waitcnt lgkmcnt(14)
	v_mfma_f32_32x32x16_bf16 v[34:49], v[150:153], v[122:125], v[34:49]
	s_waitcnt lgkmcnt(12)
	v_mfma_f32_32x32x16_bf16 v[18:33], v[150:153], v[126:129], v[18:33]
	v_add_u32_e32 v14, s47, v250
	ds_read_b128 v[194:197], v14
	ds_read_b128 v[186:189], v14 offset:512
	s_waitcnt lgkmcnt(12)
	v_mfma_f32_32x32x16_bf16 v[34:49], v[10:13], v[142:145], v[34:49]
	ds_read_b128 v[190:193], v14 offset:2048
	ds_read_b128 v[182:185], v14 offset:2560
	s_waitcnt lgkmcnt(12)
	v_mfma_f32_32x32x16_bf16 v[18:33], v[10:13], v[138:141], v[18:33]
	ds_read_b128 v[178:181], v14 offset:4096
	ds_read_b128 v[174:177], v14 offset:4608
	s_waitcnt lgkmcnt(12)
	v_mfma_f32_32x32x16_bf16 v[34:49], v[6:9], v[134:137], v[34:49]
	ds_read_b128 v[170:173], v14 offset:6144
	ds_read_b128 v[166:169], v14 offset:6656
	s_waitcnt lgkmcnt(12)
	v_mfma_f32_32x32x16_bf16 v[18:33], v[6:9], v[130:133], v[18:33]
	s_waitcnt lgkmcnt(10)
	v_mfma_f32_32x32x16_bf16 v[34:49], v[2:5], v[118:121], v[34:49]
	s_waitcnt lgkmcnt(8)
	v_mfma_f32_32x32x16_bf16 v[18:33], v[2:5], v[114:117], v[18:33]
	s_setprio 0
	s_waitcnt vmcnt(3) lgkmcnt(0)
	s_barrier
	v_exp_f32_e32 v98, v98
	v_exp_f32_e32 v99, v99
	v_exp_f32_e32 v100, v100
	v_exp_f32_e32 v101, v101
	v_exp_f32_e32 v102, v102
	v_exp_f32_e32 v103, v103
	v_exp_f32_e32 v104, v104
	v_exp_f32_e32 v105, v105
	v_exp_f32_e32 v106, v106
	v_exp_f32_e32 v107, v107
	v_exp_f32_e32 v108, v108
	v_exp_f32_e32 v109, v109
	v_exp_f32_e32 v110, v110
	v_exp_f32_e32 v111, v111
	v_exp_f32_e32 v112, v112
	v_exp_f32_e32 v113, v113
	v_exp_f32_e32 v82, v82
	v_exp_f32_e32 v83, v83
	v_exp_f32_e32 v84, v84
	v_exp_f32_e32 v85, v85
	v_exp_f32_e32 v86, v86
	v_exp_f32_e32 v87, v87
	v_exp_f32_e32 v88, v88
	v_exp_f32_e32 v89, v89
	v_exp_f32_e32 v90, v90
	v_exp_f32_e32 v91, v91
	v_exp_f32_e32 v92, v92
	v_exp_f32_e32 v93, v93
	v_exp_f32_e32 v94, v94
	v_exp_f32_e32 v95, v95
	v_exp_f32_e32 v96, v96
	v_exp_f32_e32 v97, v97
	s_add_i32 s16, s47, 0x2000
	s_cmpk_lg_i32 s47, 0x4000
	s_cselect_b32 s46, s16, 0
	s_add_i32 s16, s20, 2
	s_add_u32 s14, s14, 0x4000
	s_addc_u32 s15, s15, 0
	s_cmp_ge_u32 s16, s39
	s_cbranch_scc1 .LBB0_281
	s_mov_b32 s20, s16
	s_mov_b32 s22, s13
	s_mov_b32 s21, s47
	s_mov_b32 s13, s46
	s_branch .Lpqk2B
